# grid barrier leader path: own L1 invalidate issued with the L2 write-back, per-XCD release word no longer bumped: the leader leaves with the release like every other workgroup
# baseline (speedup 1.0000x reference)
; __device__ __forceinline__ unsigned xb_ld(unsigned* p)              { return __hip_atomic_load(p, __ATOMIC_RELAXED, __HIP_MEMORY_SCOPE_AGENT); }
; __device__ __forceinline__ unsigned xb_add(unsigned* p, unsigned v) { return __hip_atomic_fetch_add(p, v, __ATOMIC_RELAXED, __HIP_MEMORY_SCOPE_AGENT); }
; #define XB_SPIN(cond, bar) do { unsigned _sp = 0; while (cond) { __builtin_amdgcn_s_sleep(1); \
;     if ((++_sp & 255u) == 0u) { if (xb_ld(&(bar)[XB_TMO])) break; if (_sp > XB_SPIN_CAP) { atomicAdd(&(bar)[XB_TMO], 1u); break; } } } } while (0)
; __device__ __forceinline__ void xcd_barrier(const XcdBarrier& b) {
;     ...
;         if (old + 1u == (gen + 1u) * nloc) {
;             __builtin_amdgcn_fence(__ATOMIC_RELEASE, "agent");
;             asm volatile("s_waitcnt vmcnt(0)" ::: "memory");
;             const unsigned og = xb_add(&bar[XB_TOP], 1u);
;             const unsigned tg = og / nx;
;             if (og + 1u == (tg + 1u) * nx) xb_add(&bar[XB_TOPGEN], 1u);
;             else XB_SPIN(xb_ld(&bar[XB_TOPGEN]) == tg, bar);
;             __builtin_amdgcn_fence(__ATOMIC_ACQUIRE, "agent");
;             xb_add(&bar[XB_XGEN(b.x)], 1u);
;             asm volatile("s_waitcnt vmcnt(0)" ::: "memory");
.LBB0_64:
	s_andn2_saveexec_b64 s[6:7], s[6:7]
	s_cbranch_execz .LBB0_84
	s_mov_b64 s[6:7], exec
	buffer_inv sc1
	buffer_wbl2 sc1
	s_waitcnt lgkmcnt(0)
	s_waitcnt vmcnt(0)
	v_mbcnt_lo_u32_b32 v1, s6, 0
	v_mbcnt_hi_u32_b32 v1, s7, v1
	v_cmp_eq_u32_e32 vcc, 0, v1
	s_and_saveexec_b64 s[8:9], vcc
	s_cbranch_execz .LBB0_67
	s_bcnt1_i32_b64 s6, s[6:7]
	v_mov_b32_e32 v2, 0xfc3000
	v_mov_b32_e32 v3, s6
	global_atomic_add v2, v2, v3, s[50:51] offset:1024 sc0

; __device__ __forceinline__ unsigned xb_add(unsigned* p, unsigned v) { return __hip_atomic_fetch_add(p, v, __ATOMIC_RELAXED, __HIP_MEMORY_SCOPE_AGENT); }
; __device__ __forceinline__ void xcd_barrier(const XcdBarrier& b) {
;     ...
;             __builtin_amdgcn_fence(__ATOMIC_ACQUIRE, "agent");
;             xb_add(&bar[XB_XGEN(b.x)], 1u);
;             asm volatile("s_waitcnt vmcnt(0)" ::: "memory");
.LBB0_81:
	s_or_b64 exec, exec, s[6:7]
	s_mov_b64 s[6:7], exec
	v_mbcnt_lo_u32_b32 v0, s6, 0
	v_mbcnt_hi_u32_b32 v0, s7, v0
	v_cmp_eq_u32_e32 vcc, 0, v0
	s_and_saveexec_b64 s[8:9], vcc
	s_cbranch_execz .LBB0_83
	s_bcnt1_i32_b64 s6, s[6:7]
	v_mov_b32_e32 v0, 0x2000
	v_mov_b32_e32 v1, s6

; __device__ __forceinline__ unsigned xb_ld(unsigned* p)              { return __hip_atomic_load(p, __ATOMIC_RELAXED, __HIP_MEMORY_SCOPE_AGENT); }
; __device__ __forceinline__ unsigned xb_add(unsigned* p, unsigned v) { return __hip_atomic_fetch_add(p, v, __ATOMIC_RELAXED, __HIP_MEMORY_SCOPE_AGENT); }
; #define XB_SPIN(cond, bar) do { unsigned _sp = 0; while (cond) { __builtin_amdgcn_s_sleep(1); \
;     if ((++_sp & 255u) == 0u) { if (xb_ld(&(bar)[XB_TMO])) break; if (_sp > XB_SPIN_CAP) { atomicAdd(&(bar)[XB_TMO], 1u); break; } } } } while (0)
; __device__ __forceinline__ void xcd_barrier(const XcdBarrier& b) {
;     ...
;         if (old + 1u == (gen + 1u) * nloc) {
;             __builtin_amdgcn_fence(__ATOMIC_RELEASE, "agent");
;             asm volatile("s_waitcnt vmcnt(0)" ::: "memory");
;             const unsigned og = xb_add(&bar[XB_TOP], 1u);
;             const unsigned tg = og / nx;
;             if (og + 1u == (tg + 1u) * nx) xb_add(&bar[XB_TOPGEN], 1u);
;             else XB_SPIN(xb_ld(&bar[XB_TOPGEN]) == tg, bar);
.LBB0_600:
	s_andn2_saveexec_b64 s[8:9], s[8:9]
	s_cbranch_execz .LBB0_620
	s_mov_b64 s[8:9], exec
	buffer_inv sc1
	buffer_wbl2 sc1
	s_waitcnt lgkmcnt(0)
	s_waitcnt vmcnt(0)
	v_mbcnt_lo_u32_b32 v1, s8, 0
	v_mbcnt_hi_u32_b32 v1, s9, v1
	v_cmp_eq_u32_e32 vcc, 0, v1
	s_and_saveexec_b64 s[14:15], vcc
	s_cbranch_execz .LBB0_603
	s_bcnt1_i32_b64 s8, s[8:9]
	v_mov_b32_e32 v2, 0xfc3000
	v_mov_b32_e32 v3, s8
	global_atomic_add v2, v2, v3, s[50:51] offset:1024 sc0

; __device__ __forceinline__ unsigned xb_add(unsigned* p, unsigned v) { return __hip_atomic_fetch_add(p, v, __ATOMIC_RELAXED, __HIP_MEMORY_SCOPE_AGENT); }
; __device__ __forceinline__ void xcd_barrier(const XcdBarrier& b) {
;     ...
;             __builtin_amdgcn_fence(__ATOMIC_ACQUIRE, "agent");
;             xb_add(&bar[XB_XGEN(b.x)], 1u);
;             asm volatile("s_waitcnt vmcnt(0)" ::: "memory");
.LBB0_617:
	s_or_b64 exec, exec, s[8:9]
	s_mov_b64 s[8:9], exec
	v_mbcnt_lo_u32_b32 v0, s8, 0
	v_mbcnt_hi_u32_b32 v0, s9, v0
	v_cmp_eq_u32_e32 vcc, 0, v0
	s_and_saveexec_b64 s[14:15], vcc
	s_cbranch_execz .LBB0_619
	s_bcnt1_i32_b64 s8, s[8:9]
	v_mov_b32_e32 v0, 0x2000
	v_mov_b32_e32 v1, s8

; __device__ __forceinline__ unsigned xb_ld(unsigned* p)              { return __hip_atomic_load(p, __ATOMIC_RELAXED, __HIP_MEMORY_SCOPE_AGENT); }
; __device__ __forceinline__ unsigned xb_add(unsigned* p, unsigned v) { return __hip_atomic_fetch_add(p, v, __ATOMIC_RELAXED, __HIP_MEMORY_SCOPE_AGENT); }
; #define XB_SPIN(cond, bar) do { unsigned _sp = 0; while (cond) { __builtin_amdgcn_s_sleep(1); \
;     if ((++_sp & 255u) == 0u) { if (xb_ld(&(bar)[XB_TMO])) break; if (_sp > XB_SPIN_CAP) { atomicAdd(&(bar)[XB_TMO], 1u); break; } } } } while (0)
; __device__ __forceinline__ void xcd_barrier(const XcdBarrier& b) {
;     ...
;         if (old + 1u == (gen + 1u) * nloc) {
;             __builtin_amdgcn_fence(__ATOMIC_RELEASE, "agent");
;             asm volatile("s_waitcnt vmcnt(0)" ::: "memory");
;             const unsigned og = xb_add(&bar[XB_TOP], 1u);
;             const unsigned tg = og / nx;
;             if (og + 1u == (tg + 1u) * nx) xb_add(&bar[XB_TOPGEN], 1u);
;             else XB_SPIN(xb_ld(&bar[XB_TOPGEN]) == tg, bar);
.LBB0_676:
	s_andn2_saveexec_b64 s[8:9], s[8:9]
	s_cbranch_execz .LBB0_696
	s_mov_b64 s[8:9], exec
	buffer_inv sc1
	buffer_wbl2 sc1
	s_waitcnt lgkmcnt(0)
	s_waitcnt vmcnt(0)
	v_mbcnt_lo_u32_b32 v1, s8, 0
	v_mbcnt_hi_u32_b32 v1, s9, v1
	v_cmp_eq_u32_e32 vcc, 0, v1
	s_and_saveexec_b64 s[14:15], vcc
	s_cbranch_execz .LBB0_679
	s_bcnt1_i32_b64 s3, s[8:9]
	v_mov_b32_e32 v2, 0xfc3000
	v_mov_b32_e32 v3, s3
	global_atomic_add v2, v2, v3, s[50:51] offset:1024 sc0

; __device__ __forceinline__ unsigned xb_add(unsigned* p, unsigned v) { return __hip_atomic_fetch_add(p, v, __ATOMIC_RELAXED, __HIP_MEMORY_SCOPE_AGENT); }
; __device__ __forceinline__ void xcd_barrier(const XcdBarrier& b) {
;     ...
;             __builtin_amdgcn_fence(__ATOMIC_ACQUIRE, "agent");
;             xb_add(&bar[XB_XGEN(b.x)], 1u);
;             asm volatile("s_waitcnt vmcnt(0)" ::: "memory");
.LBB0_693:
	s_or_b64 exec, exec, s[8:9]
	s_mov_b64 s[8:9], exec
	v_mbcnt_lo_u32_b32 v0, s8, 0
	v_mbcnt_hi_u32_b32 v0, s9, v0
	v_cmp_eq_u32_e32 vcc, 0, v0
	s_and_saveexec_b64 s[14:15], vcc
	s_cbranch_execz .LBB0_695
	s_bcnt1_i32_b64 s3, s[8:9]
	v_mov_b32_e32 v0, 0x2000
	v_mov_b32_e32 v1, s3
